# local barriers at seams 0,4,5,7,11,12 + all-groups WAR-fence barriers (8 group counters, no L2 write-back) at seams 1,6,8; global barrier elsewhere
# baseline (speedup 1.0000x reference)
.LBB0_515:
	s_waitcnt vmcnt(0)
	s_waitcnt vmcnt(0) lgkmcnt(0)
	s_barrier
	s_and_saveexec_b64 s[0:1], s[62:63]
	s_cbranch_execz .LBB0_202
	v_readlane_b32 s8, v254, 49
	s_mov_b32 s9, 0x19f3
	s_nop 0
	s_lshr_b32 s12, s9, s8
	s_and_b32 s12, s12, s100
	s_and_b32 s12, s12, 1
	s_cmp_eq_u32 s12, 0
	s_cbranch_scc1 .Lgbar
	s_lshl_b32 s12, 2, s8
	s_sub_i32 s12, s12, 1
	s_and_b32 s12, s12, s9
	s_bcnt1_i32_b32 s12, s12
	s_lshl_b32 s9, s12, 5
	s_mov_b32 s13, 0x142
	s_lshr_b32 s13, s13, s8
	s_and_b32 s13, s13, 1
	v_readlane_b32 s8, v252, 0
	v_readlane_b32 s10, v252, 45
	v_readlane_b32 s11, v252, 46
	s_and_b32 s8, s8, 7
	s_lshl_b32 s12, 1, s8
	s_cmp_eq_u32 s13, 1
	s_cselect_b32 s13, 0xff, s12
	s_lshl_b32 s8, s8, 6
	s_add_u32 s10, s10, 0xe3600
	s_addc_u32 s11, s11, 0
	v_mov_b32_e32 v1, 1
	v_mov_b32_e32 v2, s8
	s_nop 0
	global_atomic_add v2, v1, s[10:11]
	s_mov_b64 exec, 0xff
	v_mbcnt_lo_u32_b32 v2, -1, 0
	v_lshlrev_b32_e32 v2, 6, v2
	s_mov_b32 s12, 0
.Llb_poll:
	global_load_dword v0, v2, s[10:11] sc1
	s_waitcnt vmcnt(0)
	v_cmp_le_u32_e32 vcc, s9, v0
	s_nop 1
	s_and_b32 s8, vcc_lo, s13
	s_cmp_eq_u32 s8, s13
	s_cbranch_scc1 .Llb_done
	s_sleep 1
	s_add_i32 s12, s12, 1
	s_cmp_lt_u32 s12, 0x8000
	s_cbranch_scc1 .Llb_poll
